# MoBA K/V tile LDS-DMA issue window also at priority 3 (on top of GEMM DMA-issue priority 3)
# baseline (speedup 1.0000x reference)
; __device__ void moba_item(const P& p, int bh, int qt, char* smem) {
;     ...
;   const unsigned mymask = sMask[w * 16 + li];
;   const int qpos = q0 + w * 16 + li;
;   bf16x8 qf[4];
; #pragma unroll
;   for (int kk = 0; kk < 4; ++kk) qf[kk] = *(const bf16x8*)(Q + (size_t)qpos * 128 + (kk * 4 + g) * 8);
;   f32x4 oacc[8];
; #pragma unroll
;   for (int d = 0; d < 8; ++d) oacc[d] = (f32x4){0.f, 0.f, 0.f, 0.f};
;   float mrun = -INFINITY, lrun = 0.f;
;   const int ntiles = qblk * 4 + qin + 1;
;   const int kr = tid >> 4, kc = tid & 15;
;   const int vr = tid >> 3, vc = tid & 7;
;   u32x4 rkA[4], rvA[4], rkB[4], rvB[4];
; #pragma unroll
;   for (int i = 0; i < 4; ++i) {
;     rkA[i] = *(const u32x4*)(Kp + (size_t)(kr + 16 * i) * 128 + kc * 8);
;     rvA[i] = *(const u32x4*)(VT + (size_t)(vr + 32 * i) * 4096 + vc * 8);
;   }
;   if (ntiles > 1) {
; #pragma unroll
;     for (int i = 0; i < 4; ++i) {
;       rkB[i] = *(const u32x4*)(Kp + (size_t)(64 + kr + 16 * i) * 128 + kc * 8);
;       rvB[i] = *(const u32x4*)(VT + (size_t)(vr + 32 * i) * 4096 + 64 + vc * 8);
;     }
;   }
;   const float SC = 0.12751743082459868f;
.LBB0_610:
	s_cmp_lt_i32 s40, 0
	v_lshlrev_b32_e32 v154, 3, v3
	s_cbranch_scc1 .LBB0_453
	v_lshlrev_b32_e32 v61, 7, v52
	v_xor_b32_e32 v52, v52, v2
	v_lshl_add_u64 v[156:157], v[62:63], 0, v[0:1]
	v_lshl_add_u64 v[158:159], v[68:69], 0, v[0:1]
	v_lshl_add_u64 v[160:161], v[70:71], 0, v[0:1]
	v_lshl_add_u64 v[162:163], v[72:73], 0, v[0:1]
	v_lshlrev_b32_e32 v0, 1, v76
	v_and_b32_e32 v2, 3, v2
	v_and_or_b32 v0, v0, 24, v2
	v_lshlrev_b32_e32 v155, 8, v0
	v_bitop3_b32 v0, v3, v76, 4 bitop3:0x36
	v_lshrrev_b32_e32 v53, 1, v150
	v_lshrrev_b32_e32 v74, 1, v54
	v_lshrrev_b32_e32 v75, 1, v60
	v_lshlrev_b32_e32 v178, 4, v0
	v_bitop3_b32 v0, v3, v76, 8 bitop3:0x36
	v_and_b32_e32 v53, 12, v53
	v_and_b32_e32 v74, 12, v74
	v_and_b32_e32 v75, 12, v75
	v_lshlrev_b32_e32 v179, 4, v0
	v_bitop3_b32 v0, v3, v76, 12 bitop3:0x36
	v_bitop3_b32 v53, v53, v76, v3 bitop3:0x36
	v_lshlrev_b32_e32 v52, 4, v52
	v_bitop3_b32 v74, v74, v76, v3 bitop3:0x36
	v_bitop3_b32 v75, v75, v76, v3 bitop3:0x36
	v_xor_b32_e32 v2, v3, v76
	v_lshlrev_b32_e32 v180, 4, v0
	v_xor_b32_e32 v0, v3, v77
	v_lshlrev_b32_e32 v55, 8, v150
	v_lshlrev_b32_e32 v53, 4, v53
	v_and_b32_e32 v52, 0x70, v52
	v_lshlrev_b32_e32 v54, 8, v54
	v_lshlrev_b32_e32 v74, 4, v74
	v_lshlrev_b32_e32 v60, 8, v60
	v_lshlrev_b32_e32 v75, 4, v75
	v_lshlrev_b32_e32 v151, 4, v2
	v_lshlrev_b32_e32 v182, 4, v0
	v_bitop3_b32 v0, v3, v77, 4 bitop3:0x36
	v_mov_b32_e32 v2, v1
	v_mov_b32_e32 v3, v1
	v_lshlrev_b32_e32 v181, 7, v76
	v_lshlrev_b32_e32 v183, 4, v0
	v_mov_b32_e32 v0, v1
	v_add_u32_e32 v184, v55, v53
	v_add_u32_e32 v185, v61, v52
	v_add_u32_e32 v186, v54, v74
	v_add_u32_e32 v187, v60, v75
	v_mov_b64_e32 v[106:107], v[2:3]
	v_mov_b64_e32 v[54:55], v[2:3]
	v_mov_b64_e32 v[74:75], v[2:3]
	v_mov_b64_e32 v[62:63], v[2:3]
	v_mov_b64_e32 v[78:79], v[2:3]
	v_mov_b64_e32 v[70:71], v[2:3]
	v_mov_b64_e32 v[114:115], v[2:3]
	v_mov_b64_e32 v[110:111], v[2:3]
	s_add_i32 s24, s40, -1
	s_mov_b32 s25, 0
	v_mov_b32_e32 v189, 0xff800000
	v_mov_b32_e32 v188, 0
	v_mov_b64_e32 v[104:105], v[0:1]
	v_mov_b64_e32 v[52:53], v[0:1]
	v_mov_b64_e32 v[72:73], v[0:1]
	v_mov_b64_e32 v[60:61], v[0:1]
	v_mov_b64_e32 v[76:77], v[0:1]
	v_mov_b64_e32 v[68:69], v[0:1]
	v_mov_b64_e32 v[112:113], v[0:1]
	v_mov_b64_e32 v[108:109], v[0:1]
	v_lshrrev_b32_e32 v236, 6, v208
	s_nop 0
	v_readfirstlane_b32 s79, v236
	s_lshl_b32 s79, s79, 10
	v_bfe_u32 v237, v208, 4, 2
	v_bfe_u32 v252, v208, 7, 1
	v_lshl_or_b32 v252, v252, 2, v237
	v_and_b32_e32 v253, 15, v208
	v_xor_b32_e32 v252, v252, v253
	v_lshlrev_b32_e32 v252, 4, v252
	v_lshrrev_b32_e32 v253, 4, v208
	v_lshl_or_b32 v252, v253, 8, v252
	v_xor_b32_e32 v253, 0x80, v252
	v_bfe_u32 v254, v208, 3, 3
	v_and_b32_e32 v237, 7, v208
	v_xor_b32_e32 v237, v237, v254
	v_lshlrev_b32_e32 v237, 4, v237
	v_lshl_or_b32 v254, v254, 13, v237
	s_setprio 3
	s_mov_b32 s32, s25
	v_readfirstlane_b32 s98, v152
	v_readfirstlane_b32 s99, v153
	s_lshl_b32 s57, s32, 8
	s_add_u32 s98, s98, s57
	s_addc_u32 s99, s99, 0
	s_add_u32 m0, s79, 0x0
	s_nop 0
	global_load_lds_dwordx4 v252, s[98:99]
	s_add_u32 m0, s79, 0x1000
	s_add_u32 s98, s98, 0x1000
	s_addc_u32 s99, s99, 0
	global_load_lds_dwordx4 v253, s[98:99]
	s_add_u32 m0, s79, 0x2000
	s_add_u32 s98, s98, 0x1000
	s_addc_u32 s99, s99, 0
	global_load_lds_dwordx4 v252, s[98:99]
	s_add_u32 m0, s79, 0x3000
	s_add_u32 s98, s98, 0x1000
	s_addc_u32 s99, s99, 0
	global_load_lds_dwordx4 v253, s[98:99]
	v_readfirstlane_b32 s98, v156
	v_readfirstlane_b32 s99, v157
	s_lshl_b32 s57, s32, 1
	s_add_u32 s98, s98, s57
	s_addc_u32 s99, s99, 0
	s_add_u32 m0, s79, 0x4000
	s_nop 0
	global_load_lds_dwordx4 v254, s[98:99]
	s_add_u32 m0, s79, 0x5000
	s_add_u32 s98, s98, 0x40000
	s_addc_u32 s99, s99, 0
	global_load_lds_dwordx4 v254, s[98:99]
	s_add_u32 m0, s79, 0x6000
	s_add_u32 s98, s98, 0x40000
	s_addc_u32 s99, s99, 0
	global_load_lds_dwordx4 v254, s[98:99]
	s_add_u32 m0, s79, 0x7000
	s_add_u32 s98, s98, 0x40000
	s_addc_u32 s99, s99, 0
	global_load_lds_dwordx4 v254, s[98:99]
	s_setprio 0
	s_mov_b32 s27, 0
	s_branch .LBB0_614

; __device__ void moba_item(const P& p, int bh, int qt, char* smem) {
;     ...
;     if (tt + 2 < ntiles) {
;       const int k1 = (tt + 2) * 64;
; #pragma unroll
;       for (int i = 0; i < 4; ++i) {
;         rk[i] = *(const u32x4*)(Kp + (size_t)(k1 + kr + 16 * i) * 128 + kc * 8);
;         rv[i] = *(const u32x4*)(VT + (size_t)(vr + 32 * i) * 4096 + k1 + vc * 8);
;       }
;     }
;     const int blk = tt >> 2;
;     const bool own = (blk == qblk);
;     const bool rowvalid = own || ((mymask >> blk) & 1u);
;     if (__any(rowvalid)) {
;       const int key0 = tt * 64;
;       f32x4 sacc[2][2];
; #pragma unroll
;       for (int st = 0; st < 2; ++st)
; #pragma unroll
;         for (int kt = 0; kt < 2; ++kt) {
;           sacc[st][kt] = (f32x4){0.f, 0.f, 0.f, 0.f};
;           const int row = 32 * st + 8 * (li >> 2) + 4 * kt + (li & 3);
; #pragma unroll
;           for (int kk = 0; kk < 4; ++kk) {
;             const bf16x8 kf = *(const bf16x8*)(sK + row * 256 + (((kk * 4 + g) ^ li) << 4));
;             sacc[st][kt] = __builtin_amdgcn_mfma_f32_16x16x32_bf16(kf, qf[kk], sacc[st][kt], 0, 0, 0);
;           }
;         }
;       const bool diag = (tt == ntiles - 1);
;       float mx = -INFINITY;
;       if (diag || !__all(rowvalid)) {
; #pragma unroll
;         for (int st = 0; st < 2; ++st)
; #pragma unroll
;           for (int kt = 0; kt < 2; ++kt)
; #pragma unroll
;             for (int r = 0; r < 4; ++r) {
;               const int key = key0 + 32 * st + 8 * g + 4 * kt + r;
;               bool ok = rowvalid && (!diag || key <= qpos);
;               const float sv = ok ? sacc[st][kt][r] * SC : -INFINITY;
;               sacc[st][kt][r] = sv;
;               mx = fmaxf(mx, sv);
;             }
;       } else {
; #pragma unroll
;         for (int st = 0; st < 2; ++st)
; #pragma unroll
;           for (int kt = 0; kt < 2; ++kt) {
;             sacc[st][kt] *= SC;
;             mx = fmaxf(mx, fmaxf(fmaxf(sacc[st][kt][0], sacc[st][kt][1]), fmaxf(sacc[st][kt][2], sacc[st][kt][3])));
;           }
;       }
.LBB0_616:
	s_lshr_b32 s6, s27, 2
	s_cmp_eq_u32 s6, s41
	s_cselect_b64 s[0:1], -1, 0
	s_lshl_b32 s6, 1, s6
	v_and_b32_e32 v0, s6, v149
	v_cmp_ne_u32_e32 vcc, 0, v0
	s_or_b64 s[6:7], s[0:1], vcc
	s_mov_b64 vcc, s[6:7]
	s_cbranch_vccz .LBB0_625
	v_add_u32_e32 v0, v155, v151
	v_add_u32_e32 v2, v155, v178
	v_add_u32_e32 v3, v155, v179
	v_add_u32_e32 v168, v155, v180
	s_cmp_eq_u32 s40, s27
	s_cselect_b64 s[0:1], -1, 0
	s_and_b64 vcc, exec, s[0:1]
	s_mov_b64 s[10:11], s[0:1]
	ds_read_b128 v[194:197], v0
	ds_read_b128 v[198:201], v0 offset:1024
	ds_read_b128 v[202:205], v0 offset:8192
	ds_read_b128 v[220:223], v0 offset:9216
	ds_read_b128 v[224:227], v2
	ds_read_b128 v[228:231], v2 offset:1024
	ds_read_b128 v[232:235], v2 offset:8192
	ds_read_b128 v[4:7], v2 offset:9216
	ds_read_b128 v[8:11], v3
	ds_read_b128 v[12:15], v3 offset:1024
	ds_read_b128 v[16:19], v3 offset:8192
	ds_read_b128 v[164:167], v3 offset:9216
	s_waitcnt lgkmcnt(8)
	v_mfma_f32_16x16x32_bf16 v[132:135], v[194:197], v[20:23], 0
	v_mfma_f32_16x16x32_bf16 v[140:143], v[198:201], v[20:23], 0
	v_mfma_f32_16x16x32_bf16 v[136:139], v[202:205], v[20:23], 0
	v_mfma_f32_16x16x32_bf16 v[144:147], v[220:223], v[20:23], 0
	ds_read_b128 v[194:197], v168
	ds_read_b128 v[198:201], v168 offset:1024
	ds_read_b128 v[202:205], v168 offset:8192
	ds_read_b128 v[220:223], v168 offset:9216
	s_waitcnt lgkmcnt(8)
	v_mfma_f32_16x16x32_bf16 v[132:135], v[224:227], v[24:27], v[132:135]
	v_mfma_f32_16x16x32_bf16 v[140:143], v[228:231], v[24:27], v[140:143]
	v_mfma_f32_16x16x32_bf16 v[136:139], v[232:235], v[24:27], v[136:139]
	v_mfma_f32_16x16x32_bf16 v[144:147], v[4:7], v[24:27], v[144:147]
	s_waitcnt lgkmcnt(4)
	v_mfma_f32_16x16x32_bf16 v[132:135], v[8:11], v[28:31], v[132:135]
	v_mfma_f32_16x16x32_bf16 v[140:143], v[12:15], v[28:31], v[140:143]
	v_mfma_f32_16x16x32_bf16 v[136:139], v[16:19], v[28:31], v[136:139]
	v_mfma_f32_16x16x32_bf16 v[144:147], v[164:167], v[28:31], v[144:147]
	s_waitcnt lgkmcnt(0)
	v_mfma_f32_16x16x32_bf16 v[132:135], v[194:197], v[32:35], v[132:135]
	v_mfma_f32_16x16x32_bf16 v[140:143], v[198:201], v[32:35], v[140:143]
	v_mfma_f32_16x16x32_bf16 v[136:139], v[202:205], v[32:35], v[136:139]
	v_mfma_f32_16x16x32_bf16 v[144:147], v[220:223], v[32:35], v[144:147]
	s_cmp_ge_i32 s27, s40
	s_cbranch_scc1 .Lmoba_skipA
	s_setprio 3
	s_add_i32 s32, s25, 64
	v_readfirstlane_b32 s98, v152
	v_readfirstlane_b32 s99, v153
	s_lshl_b32 s57, s32, 8
	s_add_u32 s98, s98, s57
	s_addc_u32 s99, s99, 0
	s_add_u32 m0, s79, 0x8000
	s_nop 0
	global_load_lds_dwordx4 v252, s[98:99]
	s_add_u32 m0, s79, 0x9000
	s_add_u32 s98, s98, 0x1000
	s_addc_u32 s99, s99, 0
	global_load_lds_dwordx4 v253, s[98:99]
	s_add_u32 m0, s79, 0xa000
	s_add_u32 s98, s98, 0x1000
	s_addc_u32 s99, s99, 0
	global_load_lds_dwordx4 v252, s[98:99]
	s_add_u32 m0, s79, 0xb000
	s_add_u32 s98, s98, 0x1000
	s_addc_u32 s99, s99, 0
	global_load_lds_dwordx4 v253, s[98:99]
	v_readfirstlane_b32 s98, v156
	v_readfirstlane_b32 s99, v157
	s_lshl_b32 s57, s32, 1
	s_add_u32 s98, s98, s57
	s_addc_u32 s99, s99, 0
	s_add_u32 m0, s79, 0xc000
	s_nop 0
	global_load_lds_dwordx4 v254, s[98:99]
	s_add_u32 m0, s79, 0xd000
	s_add_u32 s98, s98, 0x40000
	s_addc_u32 s99, s99, 0
	global_load_lds_dwordx4 v254, s[98:99]
	s_add_u32 m0, s79, 0xe000
	s_add_u32 s98, s98, 0x40000
	s_addc_u32 s99, s99, 0
	global_load_lds_dwordx4 v254, s[98:99]
	s_add_u32 m0, s79, 0xf000
	s_add_u32 s98, s98, 0x40000
	s_addc_u32 s99, s99, 0
	global_load_lds_dwordx4 v254, s[98:99]
	s_setprio 0
	.Lmoba_skipA:
	s_nop 7
	s_cbranch_vccnz .LBB0_620
	v_cndmask_b32_e64 v4, v244, 0, s[6:7]
	s_mov_b32 s28, 0x3e0293ee
	v_pk_fma_f32 v[164:165], v[134:135], s[28:29], v[4:5] op_sel_hi:[1,0,0]
	v_pk_fma_f32 v[168:169], v[142:143], s[28:29], v[4:5] op_sel_hi:[1,0,0]
	v_pk_fma_f32 v[2:3], v[132:133], s[28:29], v[4:5] op_sel_hi:[1,0,0]
	v_max_f32_e32 v0, v164, v165
	v_pk_fma_f32 v[166:167], v[140:141], s[28:29], v[4:5] op_sel_hi:[1,0,0]
	v_max_f32_e32 v170, v168, v169
	v_max3_f32 v0, v2, v3, v0
	v_max3_f32 v170, v166, v167, v170
	s_mov_b32 s10, 0xff800000
	v_pk_fma_f32 v[172:173], v[138:139], s[28:29], v[4:5] op_sel_hi:[1,0,0]
	v_max3_f32 v0, v0, s10, v170
	v_pk_fma_f32 v[170:171], v[136:137], s[28:29], v[4:5] op_sel_hi:[1,0,0]
	v_max_f32_e32 v174, v172, v173
	v_pk_fma_f32 v[176:177], v[146:147], s[28:29], v[4:5] op_sel_hi:[1,0,0]
	v_max3_f32 v190, v170, v171, v174
	v_pk_fma_f32 v[174:175], v[144:145], s[28:29], v[4:5] op_sel_hi:[1,0,0]
	v_max_f32_e32 v191, v176, v177
	v_max3_f32 v191, v174, v175, v191
	v_max3_f32 v0, v0, v190, v191
	s_mov_b64 s[10:11], 0

; __device__ void moba_item(const P& p, int bh, int qt, char* smem) {
;     ...
;     if (tt + 2 < ntiles) {
;       const int k1 = (tt + 2) * 64;
; #pragma unroll
;       for (int i = 0; i < 4; ++i) {
;         rk[i] = *(const u32x4*)(Kp + (size_t)(k1 + kr + 16 * i) * 128 + kc * 8);
;         rv[i] = *(const u32x4*)(VT + (size_t)(vr + 32 * i) * 4096 + k1 + vc * 8);
;       }
;     }
.Lmoba_lateB:
	s_cmp_lg_u32 s8, 0
	s_cbranch_scc1 .Lmoba_skipB2
	s_setprio 3
	s_add_i32 s32, s25, 128
	v_readfirstlane_b32 s98, v152
	v_readfirstlane_b32 s99, v153
	s_lshl_b32 s57, s32, 8
	s_add_u32 s98, s98, s57
	s_addc_u32 s99, s99, 0
	s_add_u32 m0, s79, 0x0
	s_nop 0
	global_load_lds_dwordx4 v252, s[98:99]
	s_add_u32 m0, s79, 0x1000
	s_add_u32 s98, s98, 0x1000
	s_addc_u32 s99, s99, 0
	global_load_lds_dwordx4 v253, s[98:99]
	s_add_u32 m0, s79, 0x2000
	s_add_u32 s98, s98, 0x1000
	s_addc_u32 s99, s99, 0
	global_load_lds_dwordx4 v252, s[98:99]
	s_add_u32 m0, s79, 0x3000
	s_add_u32 s98, s98, 0x1000
	s_addc_u32 s99, s99, 0
	global_load_lds_dwordx4 v253, s[98:99]
	v_readfirstlane_b32 s98, v156
	v_readfirstlane_b32 s99, v157
	s_lshl_b32 s57, s32, 1
	s_add_u32 s98, s98, s57
	s_addc_u32 s99, s99, 0
	s_add_u32 m0, s79, 0x4000
	s_nop 0
	global_load_lds_dwordx4 v254, s[98:99]
	s_add_u32 m0, s79, 0x5000
	s_add_u32 s98, s98, 0x40000
	s_addc_u32 s99, s99, 0
	global_load_lds_dwordx4 v254, s[98:99]
	s_add_u32 m0, s79, 0x6000
	s_add_u32 s98, s98, 0x40000
	s_addc_u32 s99, s99, 0
	global_load_lds_dwordx4 v254, s[98:99]
	s_add_u32 m0, s79, 0x7000
	s_add_u32 s98, s98, 0x40000
	s_addc_u32 s99, s99, 0
	global_load_lds_dwordx4 v254, s[98:99]
	s_setprio 0

; __device__ void moba_item(const P& p, int bh, int qt, char* smem) {
;     ...
;     if (tt + 2 < ntiles) {
;       const int k1 = (tt + 2) * 64;
; #pragma unroll
;       for (int i = 0; i < 4; ++i) {
;         rk[i] = *(const u32x4*)(Kp + (size_t)(k1 + kr + 16 * i) * 128 + kc * 8);
;         rv[i] = *(const u32x4*)(VT + (size_t)(vr + 32 * i) * 4096 + k1 + vc * 8);
;       }
;     }
.LBB0_625:
	s_cmp_ge_i32 s27, s40
	s_cbranch_scc1 .Lmoba_skipA2
	s_setprio 3
	s_add_i32 s32, s25, 64
	v_readfirstlane_b32 s98, v152
	v_readfirstlane_b32 s99, v153
	s_lshl_b32 s57, s32, 8
	s_add_u32 s98, s98, s57
	s_addc_u32 s99, s99, 0
	s_add_u32 m0, s79, 0x8000
	s_nop 0
	global_load_lds_dwordx4 v252, s[98:99]
	s_add_u32 m0, s79, 0x9000
	s_add_u32 s98, s98, 0x1000
	s_addc_u32 s99, s99, 0
	global_load_lds_dwordx4 v253, s[98:99]
	s_add_u32 m0, s79, 0xa000
	s_add_u32 s98, s98, 0x1000
	s_addc_u32 s99, s99, 0
	global_load_lds_dwordx4 v252, s[98:99]
	s_add_u32 m0, s79, 0xb000
	s_add_u32 s98, s98, 0x1000
	s_addc_u32 s99, s99, 0
	global_load_lds_dwordx4 v253, s[98:99]
	v_readfirstlane_b32 s98, v156
	v_readfirstlane_b32 s99, v157
	s_lshl_b32 s57, s32, 1
	s_add_u32 s98, s98, s57
	s_addc_u32 s99, s99, 0
	s_add_u32 m0, s79, 0xc000
	s_nop 0
	global_load_lds_dwordx4 v254, s[98:99]
	s_add_u32 m0, s79, 0xd000
	s_add_u32 s98, s98, 0x40000
	s_addc_u32 s99, s99, 0
	global_load_lds_dwordx4 v254, s[98:99]
	s_add_u32 m0, s79, 0xe000
	s_add_u32 s98, s98, 0x40000
	s_addc_u32 s99, s99, 0
	global_load_lds_dwordx4 v254, s[98:99]
	s_add_u32 m0, s79, 0xf000
	s_add_u32 s98, s98, 0x40000
	s_addc_u32 s99, s99, 0
	global_load_lds_dwordx4 v254, s[98:99]
	s_setprio 0

; __device__ void moba_item(const P& p, int bh, int qt, char* smem) {
;     ...
;     if (tt + 2 < ntiles) {
;       const int k1 = (tt + 2) * 64;
; #pragma unroll
;       for (int i = 0; i < 4; ++i) {
;         rk[i] = *(const u32x4*)(Kp + (size_t)(k1 + kr + 16 * i) * 128 + kc * 8);
;         rv[i] = *(const u32x4*)(VT + (size_t)(vr + 32 * i) * 4096 + k1 + vc * 8);
;       }
;     }
;     const int blk = tt >> 2;
;     const bool own = (blk == qblk);
;     const bool rowvalid = own || ((mymask >> blk) & 1u);
;     if (__any(rowvalid)) {
;       const int key0 = tt * 64;
;       f32x4 sacc[2][2];
; #pragma unroll
;       for (int st = 0; st < 2; ++st)
; #pragma unroll
;         for (int kt = 0; kt < 2; ++kt) {
;           sacc[st][kt] = (f32x4){0.f, 0.f, 0.f, 0.f};
;           const int row = 32 * st + 8 * (li >> 2) + 4 * kt + (li & 3);
; #pragma unroll
;           for (int kk = 0; kk < 4; ++kk) {
;             const bf16x8 kf = *(const bf16x8*)(sK + row * 256 + (((kk * 4 + g) ^ li) << 4));
;             sacc[st][kt] = __builtin_amdgcn_mfma_f32_16x16x32_bf16(kf, qf[kk], sacc[st][kt], 0, 0, 0);
;           }
;         }
;       const bool diag = (tt == ntiles - 1);
;       float mx = -INFINITY;
;       if (diag || !__all(rowvalid)) {
; #pragma unroll
;         for (int st = 0; st < 2; ++st)
; #pragma unroll
;           for (int kt = 0; kt < 2; ++kt)
; #pragma unroll
;             for (int r = 0; r < 4; ++r) {
;               const int key = key0 + 32 * st + 8 * g + 4 * kt + r;
;               bool ok = rowvalid && (!diag || key <= qpos);
;               const float sv = ok ? sacc[st][kt][r] * SC : -INFINITY;
;               sacc[st][kt][r] = sv;
;               mx = fmaxf(mx, sv);
;             }
;       } else {
; #pragma unroll
;         for (int st = 0; st < 2; ++st)
; #pragma unroll
;           for (int kt = 0; kt < 2; ++kt) {
;             sacc[st][kt] *= SC;
;             mx = fmaxf(mx, fmaxf(fmaxf(sacc[st][kt][0], sacc[st][kt][1]), fmaxf(sacc[st][kt][2], sacc[st][kt][3])));
;           }
;       }
.LBB0_628:
	v_cndmask_b32_e64 v0, 0, 1, s[6:7]
	v_cmp_ne_u32_e32 vcc, 0, v0
	s_cbranch_vccz .Lmoba_lateB
	v_add_u32_e32 v2, v155, v151
	v_add_u32_e32 v3, v155, v178
	v_add_u32_e32 v168, v155, v179
	v_add_u32_e32 v169, v155, v180
	s_cmp_eq_u32 s24, s27
	s_cselect_b64 s[0:1], -1, 0
	s_and_b64 vcc, exec, s[0:1]
	s_mov_b64 s[10:11], s[0:1]
	ds_read_b128 v[194:197], v2 offset:32768
	ds_read_b128 v[198:201], v2 offset:33792
	ds_read_b128 v[202:205], v2 offset:40960
	ds_read_b128 v[220:223], v2 offset:41984
	ds_read_b128 v[224:227], v3 offset:32768
	ds_read_b128 v[228:231], v3 offset:33792
	ds_read_b128 v[232:235], v3 offset:40960
	ds_read_b128 v[4:7], v3 offset:41984
	ds_read_b128 v[8:11], v168 offset:32768
	ds_read_b128 v[12:15], v168 offset:33792
	ds_read_b128 v[16:19], v168 offset:40960
	ds_read_b128 v[164:167], v168 offset:41984
	s_waitcnt lgkmcnt(8)
	v_mfma_f32_16x16x32_bf16 v[132:135], v[194:197], v[20:23], 0
	v_mfma_f32_16x16x32_bf16 v[140:143], v[198:201], v[20:23], 0
	v_mfma_f32_16x16x32_bf16 v[136:139], v[202:205], v[20:23], 0
	v_mfma_f32_16x16x32_bf16 v[144:147], v[220:223], v[20:23], 0
	ds_read_b128 v[194:197], v169 offset:32768
	ds_read_b128 v[198:201], v169 offset:33792
	ds_read_b128 v[202:205], v169 offset:40960
	ds_read_b128 v[220:223], v169 offset:41984
	s_waitcnt lgkmcnt(8)
	v_mfma_f32_16x16x32_bf16 v[132:135], v[224:227], v[24:27], v[132:135]
	v_mfma_f32_16x16x32_bf16 v[140:143], v[228:231], v[24:27], v[140:143]
	v_mfma_f32_16x16x32_bf16 v[136:139], v[232:235], v[24:27], v[136:139]
	v_mfma_f32_16x16x32_bf16 v[144:147], v[4:7], v[24:27], v[144:147]
	s_waitcnt lgkmcnt(4)
	v_mfma_f32_16x16x32_bf16 v[132:135], v[8:11], v[28:31], v[132:135]
	v_mfma_f32_16x16x32_bf16 v[140:143], v[12:15], v[28:31], v[140:143]
	v_mfma_f32_16x16x32_bf16 v[136:139], v[16:19], v[28:31], v[136:139]
	v_mfma_f32_16x16x32_bf16 v[144:147], v[164:167], v[28:31], v[144:147]
	s_waitcnt lgkmcnt(0)
	v_mfma_f32_16x16x32_bf16 v[132:135], v[194:197], v[32:35], v[132:135]
	v_mfma_f32_16x16x32_bf16 v[140:143], v[198:201], v[32:35], v[140:143]
	v_mfma_f32_16x16x32_bf16 v[136:139], v[202:205], v[32:35], v[136:139]
	v_mfma_f32_16x16x32_bf16 v[144:147], v[220:223], v[32:35], v[144:147]
	s_cmp_lg_u32 s8, 0
	s_cbranch_scc1 .Lmoba_skipB
	s_setprio 3
	s_add_i32 s32, s25, 128
	v_readfirstlane_b32 s98, v152
	v_readfirstlane_b32 s99, v153
	s_lshl_b32 s57, s32, 8
	s_add_u32 s98, s98, s57
	s_addc_u32 s99, s99, 0
	s_add_u32 m0, s79, 0x0
	s_nop 0
	global_load_lds_dwordx4 v252, s[98:99]
	s_add_u32 m0, s79, 0x1000
	s_add_u32 s98, s98, 0x1000
	s_addc_u32 s99, s99, 0
	global_load_lds_dwordx4 v253, s[98:99]
	s_add_u32 m0, s79, 0x2000
	s_add_u32 s98, s98, 0x1000
	s_addc_u32 s99, s99, 0
	global_load_lds_dwordx4 v252, s[98:99]
	s_add_u32 m0, s79, 0x3000
	s_add_u32 s98, s98, 0x1000
	s_addc_u32 s99, s99, 0
	global_load_lds_dwordx4 v253, s[98:99]
	v_readfirstlane_b32 s98, v156
	v_readfirstlane_b32 s99, v157
	s_lshl_b32 s57, s32, 1
	s_add_u32 s98, s98, s57
	s_addc_u32 s99, s99, 0
	s_add_u32 m0, s79, 0x4000
	s_nop 0
	global_load_lds_dwordx4 v254, s[98:99]
	s_add_u32 m0, s79, 0x5000
	s_add_u32 s98, s98, 0x40000
	s_addc_u32 s99, s99, 0
	global_load_lds_dwordx4 v254, s[98:99]
	s_add_u32 m0, s79, 0x6000
	s_add_u32 s98, s98, 0x40000
	s_addc_u32 s99, s99, 0
	global_load_lds_dwordx4 v254, s[98:99]
	s_add_u32 m0, s79, 0x7000
	s_add_u32 s98, s98, 0x40000
	s_addc_u32 s99, s99, 0
	global_load_lds_dwordx4 v254, s[98:99]
	s_setprio 0
	.Lmoba_skipB:
	s_nop 7
	s_cbranch_vccnz .LBB0_632
	v_cndmask_b32_e64 v4, v244, 0, s[6:7]
	s_mov_b32 s28, 0x3e0293ee
	v_pk_fma_f32 v[164:165], v[134:135], s[28:29], v[4:5] op_sel_hi:[1,0,0]
	v_pk_fma_f32 v[2:3], v[132:133], s[28:29], v[4:5] op_sel_hi:[1,0,0]
	v_max_f32_e32 v166, v164, v165
	v_pk_fma_f32 v[168:169], v[142:143], s[28:29], v[4:5] op_sel_hi:[1,0,0]
	v_max3_f32 v170, v2, v3, v166
	v_pk_fma_f32 v[166:167], v[140:141], s[28:29], v[4:5] op_sel_hi:[1,0,0]
	v_max_f32_e32 v171, v168, v169
	v_max3_f32 v171, v166, v167, v171
	s_mov_b32 s10, 0xff800000
	v_pk_fma_f32 v[172:173], v[138:139], s[28:29], v[4:5] op_sel_hi:[1,0,0]
	v_max3_f32 v189, v170, s10, v171
	v_pk_fma_f32 v[170:171], v[136:137], s[28:29], v[4:5] op_sel_hi:[1,0,0]
	v_max_f32_e32 v174, v172, v173
	v_pk_fma_f32 v[176:177], v[146:147], s[28:29], v[4:5] op_sel_hi:[1,0,0]
	v_max3_f32 v191, v170, v171, v174
	v_pk_fma_f32 v[174:175], v[144:145], s[28:29], v[4:5] op_sel_hi:[1,0,0]
	v_max_f32_e32 v192, v176, v177
	v_max3_f32 v192, v174, v175, v192
	v_max3_f32 v189, v189, v191, v192
	s_mov_b64 s[10:11], 0
